# v37 + early partial L2 write-back by every 8th non-leader arrival
# baseline (speedup 1.0000x reference)
; DI void gbar(unsigned* ctr, unsigned& gen, unsigned G) {
;     asm volatile("s_waitcnt vmcnt(0)" ::: "memory");
;     __syncthreads();
;     gen += 1;
;     if (threadIdx.x == 0) {
;         __builtin_amdgcn_fence(__ATOMIC_RELEASE, "agent");
;         asm volatile("s_waitcnt vmcnt(0)" ::: "memory");
;         __hip_atomic_fetch_add(ctr, 1u, __ATOMIC_RELAXED, __HIP_MEMORY_SCOPE_AGENT);
;         while (__hip_atomic_load(ctr, __ATOMIC_RELAXED, __HIP_MEMORY_SCOPE_AGENT) < gen * G) __builtin_amdgcn_s_sleep(32);
.Lxb_nle_0:
	v_and_b32_e32 v8, 7, v4
	v_cmp_eq_u32_e32 vcc, 0, v8
	s_cbranch_vccz .Lxb_nl_0
	buffer_wbl2 sc1
